# P6 queue: static longest-first pre-assignment (SSD prompt items per bid%8 plus the four line-sharing S5 pass-2 items on workgroups 192..255), tickets for the rest
# baseline (speedup 1.0000x reference)
.LBB0_1066:
	v_writelane_b32 v251, s36, 50
	v_writelane_b32 v253, s79, 0
	v_writelane_b32 v253, s78, 1
	v_writelane_b32 v251, s37, 51
	v_writelane_b32 v251, s54, 52
	v_writelane_b32 v253, s76, 2
	s_nop 0
	v_writelane_b32 v251, s55, 53
	v_writelane_b32 v253, s77, 3
	v_writelane_b32 v251, s96, 54
	v_writelane_b32 v253, s69, 4
	v_writelane_b32 v251, s97, 55
	v_writelane_b32 v253, s72, 5
	v_writelane_b32 v251, s66, 56
	s_nop 0
	v_writelane_b32 v253, s73, 6
	v_writelane_b32 v251, s67, 57
	v_writelane_b32 v253, s70, 7
	v_writelane_b32 v251, s75, 58
	v_writelane_b32 v251, s74, 59
	v_writelane_b32 v253, s71, 8
	v_writelane_b32 v253, s68, 9
	v_writelane_b32 v251, s59, 60
	v_writelane_b32 v253, s58, 10
	v_writelane_b32 v251, s60, 61
	s_nop 0
	v_writelane_b32 v253, s59, 11
	v_writelane_b32 v251, s61, 62
	v_writelane_b32 v253, s56, 12
	v_writelane_b32 v251, s63, 63
	s_nop 0
	v_writelane_b32 v253, s57, 13
	s_or_b64 exec, exec, s[30:31]
	v_readlane_b32 s0, v251, 10
	s_add_i32 s1, s0, 0xffffe200
	v_writelane_b32 v253, s1, 14
	s_lshl_b32 s1, s0, 8
	s_cmp_gt_u32 s62, 63
	v_writelane_b32 v253, s1, 15
	s_cselect_b64 s[2:3], -1, 0
	v_writelane_b32 v253, s2, 16
	s_cmp_eq_u32 s0, 7
	s_cselect_b64 s[0:1], -1, 0
	v_writelane_b32 v253, s3, 17
	s_add_u32 s56, s40, 0x4a5c000
	v_writelane_b32 v253, s0, 18
	s_addc_u32 s57, s41, 0
	s_mov_b64 s[34:35], s[64:65]
	v_writelane_b32 v253, s1, 19
	s_add_u32 s0, s40, 0x4220000
	v_writelane_b32 v253, s0, 20
	s_addc_u32 s0, s41, 0
	v_writelane_b32 v253, s0, 21
	s_add_i32 s0, 0, 0x22000
	v_writelane_b32 v253, s0, 22
	s_add_i32 s0, 0, 0x11000
	v_writelane_b32 v253, s0, 23
	s_add_i32 s0, 0, 0x19800
	v_writelane_b32 v253, s0, 24
	s_add_i32 s0, 0, 0x1dc00
	v_writelane_b32 v253, s0, 25
	s_add_i32 s0, 0, 0x2643c
	v_writelane_b32 v253, s0, 26
	s_add_i32 s0, 0, 0x2647c
	v_writelane_b32 v253, s0, 27
	s_add_i32 s0, 0, 0x264bc
	v_writelane_b32 v253, s0, 28
	s_add_i32 s0, 0, 0x264fc
	v_writelane_b32 v253, s0, 29
	s_add_i32 s0, 0, 0x2653c
	v_writelane_b32 v253, s0, 30
	s_add_i32 s0, 0, 0x2657c
	v_writelane_b32 v253, s0, 31
	s_add_i32 s0, 0, 0x265bc
	v_writelane_b32 v253, s0, 32
	s_add_i32 s0, 0, 0x265fc
	v_writelane_b32 v253, s0, 33
	v_writelane_b32 v253, s34, 34
	v_readlane_b32 s36, v252, 48
	v_readlane_b32 s42, v252, 54
	v_writelane_b32 v253, s35, 35
	v_readlane_b32 s43, v252, 55
	v_readlane_b32 s48, v252, 60
	v_readlane_b32 s49, v252, 61
	v_readlane_b32 s50, v252, 62
	v_readlane_b32 s51, v252, 63
	v_writelane_b32 v253, s56, 36
	v_mov_b32_e32 v187, 0
	s_add_i32 s76, 0, 0x26a00
	v_readlane_b32 s48, v251, 0
	v_readlane_b32 s42, v251, 37
	v_writelane_b32 v253, s57, 37
	s_mov_b32 s81, 0
	s_movk_i32 s77, 0x2600
	s_movk_i32 s78, 0x1000
	s_mov_b32 s33, 0xbfb8aa3b
	v_mov_b32_e32 v199, 0x3eaaaaab
	s_mov_b32 s58, 0x800000
	s_mov_b32 s59, 0x3f317217
	s_mov_b32 s96, 0x7f800000
	s_mov_b32 s97, 0x3dcccccd
	s_movk_i32 s79, 0x2000
	v_mov_b32_e32 v200, s76
	v_mbcnt_hi_u32_b32 v198, -1, v250
	v_mov_b32_e32 v201, 0x41b17218
	v_mov_b32_e32 v0, v187
	v_mov_b32_e32 v1, v187
	v_mov_b32_e32 v2, v187
	v_mov_b32_e32 v3, v187
	v_bfrev_b32_e32 v202, 0.5
	v_readlane_b32 s37, v252, 49
	v_readlane_b32 s38, v252, 50
	v_readlane_b32 s39, v252, 51
	v_readlane_b32 s40, v252, 52
	v_readlane_b32 s41, v252, 53
	v_readlane_b32 s49, v251, 1
	v_readlane_b32 s50, v251, 2
	v_readlane_b32 s51, v251, 3
	v_readlane_b32 s52, v251, 4
	v_readlane_b32 s53, v251, 5
	v_readlane_b32 s54, v251, 6
	v_readlane_b32 s55, v251, 7
	v_readlane_b32 s43, v251, 38
	v_writelane_b32 v253, s76, 38
	s_waitcnt lgkmcnt(0)
	s_barrier
	v_readlane_b32 s44, v252, 56
	v_readlane_b32 s45, v252, 57
	v_readlane_b32 s46, v252, 58
	v_readlane_b32 s47, v252, 59
	v_readlane_b32 s98, v251, 19
	s_lshr_b32 s98, s98, 3
	s_and_b32 s100, s98, 7
	s_lshr_b32 s101, s98, 3
	s_mul_i32 s99, s100, 24
	s_add_i32 s99, s99, s101
	s_lshl_b32 s100, s100, 5
	s_sub_i32 s101, s101, 24
	s_lshl_b32 s101, s101, 2
	s_add_i32 s100, s100, s101
	s_addk_i32 s100, 0x2c0
	s_cmpk_lt_u32 s98, 0xc0
	s_cselect_b32 s98, s99, s100
	s_cselect_b32 s99, 1, 4
	s_branch .LBB0_1070

.LBB0_1070:
	s_barrier
	s_cmp_lt_i32 s98, 0
	s_cbranch_scc1 .Lq_pop
	v_mov_b32_e32 v4, s98
	s_add_i32 s98, s98, 1
	s_sub_i32 s99, s99, 1
	s_cmp_gt_i32 s99, 0
	s_cselect_b32 s98, s98, -1
	s_branch .Lq_have

.LBB0_1074:
	s_or_b64 exec, exec, s[0:1]
	s_waitcnt lgkmcnt(0)
	s_barrier
	ds_read_b32 v4, v200
	s_waitcnt lgkmcnt(0)
	v_add_u32_e32 v4, 0xc0, v4
	v_cmp_lt_u32_e32 vcc, 0x2bf, v4
	v_cndmask_b32_e64 v5, 0, 1, vcc
	v_lshl_add_u32 v4, v5, 8, v4
